# GLA finalize between attention units: gate division by v_rcp_f32 * r instead of the IEEE division sequence
# baseline (speedup 1.0000x reference)
; __device__ __forceinline__ void p3b_finalize(Frame& F, bool dummy, int gw, int NGW, int MEND) {
;     ...
;         for (int h = 0; h < 4; ++h) {
;             const float x[8] = {bflo(raw[h].x), bfhi(raw[h].x), bflo(raw[h].y), bfhi(raw[h].y), bflo(raw[h].z), bfhi(raw[h].z), bflo(raw[h].w), bfhi(raw[h].w)};
;             const float gg[8] = {bflo(gr[h].x), bfhi(gr[h].x), bflo(gr[h].y), bfhi(gr[h].y), bflo(gr[h].z), bfhi(gr[h].z), bflo(gr[h].w), bfhi(gr[h].w)};
;             float ss = 0.f;
; #pragma unroll
;             for (int e = 0; e < 8; ++e) ss += x[e] * x[e];
;             ss = wave_sum(ss); const float rs = rsqrtf(ss * (1.f / 512.f) + LN_EPS);
;             float y[8];
; #pragma unroll
;             for (int e = 0; e < 8; ++e) { const float gn = e < 4 ? g0[e & 3] : g1[e & 3]; const float sl = gg[e] / (1.f + __expf(-gg[e])); y[e] = x[e] * rs * gn * sl; }
.LBB0_1111:
	v_and_b32_e32 v87, 0xffff0000, v64
	v_lshlrev_b32_e32 v0, 16, v65
	v_lshlrev_b32_e32 v85, 16, v64
	v_and_b32_e32 v86, 0xffff0000, v65
	v_mul_f32_e32 v65, 0xbfb8aa3b, v87
	v_mul_f32_e32 v64, 0xbfb8aa3b, v85
	v_exp_f32_e32 v84, v65
	v_mul_f32_e32 v65, 0xbfb8aa3b, v0
	v_exp_f32_e32 v64, v64
	v_exp_f32_e32 v65, v65
	v_and_b32_e32 v96, 0xffff0000, v67
	v_and_b32_e32 v97, 0xffff0000, v66
	v_lshlrev_b32_e32 v83, 16, v69
	v_pk_add_f32 v[64:65], v[64:65], 1.0 op_sel_hi:[1,0]
	v_lshlrev_b32_e32 v82, 16, v68
	v_and_b32_e32 v69, 0xffff0000, v69
	v_and_b32_e32 v68, 0xffff0000, v68
	v_pk_mul_f32 v[4:5], v[82:83], v[82:83]
	v_rcp_f32_e32 v88, v65
	s_nop 0
	v_mul_f32_e32 v65, v0, v88
	v_pk_mul_f32 v[90:91], v[68:69], v[68:69]
	v_and_b32_e32 v108, 0xffff0000, v58
	v_rcp_f32_e32 v0, v64
	s_nop 0
	v_mul_f32_e32 v64, v85, v0
	v_mul_f32_e32 v0, 0xbfb8aa3b, v86
	v_exp_f32_e32 v85, v0
	s_nop 0
	v_pk_add_f32 v[84:85], v[84:85], 1.0 op_sel_hi:[1,0]
	s_nop 0
	s_nop 0
	v_rcp_f32_e32 v0, v85
	s_nop 0
	v_mul_f32_e32 v85, v86, v0
	s_nop 0
	v_lshlrev_b32_e32 v86, 16, v70
	v_and_b32_e32 v70, 0xffff0000, v70
	v_rcp_f32_e32 v0, v84
	s_nop 0
	v_mul_f32_e32 v84, v87, v0
	v_lshlrev_b32_e32 v87, 16, v71
	v_and_b32_e32 v71, 0xffff0000, v71
	v_lshlrev_b32_e32 v0, 16, v67
	v_lshlrev_b32_e32 v89, 16, v66
	v_mov_b32_e32 v66, v70
	v_mov_b32_e32 v67, v86
	v_pk_mul_f32 v[92:93], v[66:67], v[66:67]
	v_mov_b32_e32 v66, v71
	v_mov_b32_e32 v67, v87
	v_pk_mul_f32 v[94:95], v[66:67], v[66:67]
	v_mul_f32_e32 v67, 0xbfb8aa3b, v97
	v_mul_f32_e32 v66, 0xbfb8aa3b, v89
	v_exp_f32_e32 v88, v67
	v_mul_f32_e32 v67, 0xbfb8aa3b, v0
	v_exp_f32_e32 v66, v66
	v_exp_f32_e32 v67, v67
	s_nop 0
	v_pk_add_f32 v[66:67], v[66:67], 1.0 op_sel_hi:[1,0]
	s_nop 0
	s_nop 0
	v_rcp_f32_e32 v98, v67
	s_nop 0
	v_mul_f32_e32 v67, v0, v98
	s_nop 0
	v_rcp_f32_e32 v0, v66
	s_nop 0
	v_mul_f32_e32 v66, v89, v0
	v_mul_f32_e32 v0, 0xbfb8aa3b, v96
	v_exp_f32_e32 v89, v0
	s_nop 0
	v_pk_add_f32 v[88:89], v[88:89], 1.0 op_sel_hi:[1,0]
	s_nop 0
	s_nop 0
	v_rcp_f32_e32 v0, v89
	s_nop 0
	v_mul_f32_e32 v89, v96, v0
	s_nop 0
	v_rcp_f32_e32 v0, v88
	s_nop 0
	v_mul_f32_e32 v88, v97, v0
	v_add_f32_e32 v0, v4, v90
	v_add_f32_e32 v0, v5, v0
	v_add_f32_e32 v0, v91, v0
	v_add_f32_e32 v0, v93, v0
	v_add_f32_e32 v0, v92, v0
	v_add_f32_e32 v0, v95, v0
	v_add_f32_e32 v0, v94, v0
	v_and_b32_e32 v100, 0xffff0000, v56
	v_and_b32_e32 v92, 0xffff0000, v57
	v_add_f32_dpp v0, v0, v0 quad_perm:[1,0,3,2] row_mask:0xf bank_mask:0xf bound_ctrl:1
	v_lshlrev_b32_e32 v91, 16, v61
	v_lshlrev_b32_e32 v90, 16, v60
	v_add_f32_dpp v0, v0, v0 quad_perm:[2,3,0,1] row_mask:0xf bank_mask:0xf bound_ctrl:1
	v_and_b32_e32 v61, 0xffff0000, v61
	v_and_b32_e32 v60, 0xffff0000, v60
	v_add_f32_dpp v0, v0, v0 row_half_mirror row_mask:0xf bank_mask:0xf bound_ctrl:1
	v_pk_mul_f32 v[94:95], v[90:91], v[90:91]
	v_pk_mul_f32 v[96:97], v[60:61], v[60:61]
	v_add_f32_dpp v0, v0, v0 row_ror:8 row_mask:0xf bank_mask:0xf bound_ctrl:1
	ds_swizzle_b32 v4, v0 offset:swizzle(SWAP,16)
	s_waitcnt lgkmcnt(0)
	v_add_f32_e32 v5, v0, v4
	v_lshlrev_b32_e32 v0, 16, v57
	v_lshlrev_b32_e32 v4, 16, v56
	v_mul_f32_e32 v57, 0xbfb8aa3b, v100
	v_mul_f32_e32 v56, 0xbfb8aa3b, v4
	v_exp_f32_e32 v98, v57
	v_mul_f32_e32 v57, 0xbfb8aa3b, v0
	v_exp_f32_e32 v56, v56
	v_exp_f32_e32 v57, v57
	v_mov_b32_e32 v93, v5
	s_nop 1
	v_permlane32_swap_b32_e32 v5, v93
	v_pk_add_f32 v[56:57], v[56:57], 1.0 op_sel_hi:[1,0]
	s_nop 0
	s_nop 0
	v_rcp_f32_e32 v99, v57
	s_nop 0
	v_mul_f32_e32 v57, v0, v99
	s_nop 0
	v_rcp_f32_e32 v0, v56
	s_nop 0
	v_mul_f32_e32 v56, v4, v0
	v_mul_f32_e32 v0, 0xbfb8aa3b, v92
	v_exp_f32_e32 v99, v0
	s_nop 0
	v_pk_add_f32 v[98:99], v[98:99], 1.0 op_sel_hi:[1,0]
	s_nop 0
	s_nop 0
	v_rcp_f32_e32 v0, v99
	s_nop 0
	v_mul_f32_e32 v99, v92, v0
	s_nop 0
	v_rcp_f32_e32 v0, v98
	s_nop 0
	v_mul_f32_e32 v98, v100, v0
	v_lshlrev_b32_e32 v100, 16, v62
	v_and_b32_e32 v62, 0xffff0000, v62
	v_lshlrev_b32_e32 v101, 16, v63
	v_and_b32_e32 v63, 0xffff0000, v63
	v_lshlrev_b32_e32 v0, 16, v59
	v_lshlrev_b32_e32 v4, 16, v58
	v_and_b32_e32 v92, 0xffff0000, v59
	v_mov_b32_e32 v58, v62
	v_mov_b32_e32 v59, v100
	v_pk_mul_f32 v[102:103], v[58:59], v[58:59]
	v_mov_b32_e32 v58, v63
	v_mov_b32_e32 v59, v101
	v_pk_mul_f32 v[104:105], v[58:59], v[58:59]
	v_mul_f32_e32 v59, 0xbfb8aa3b, v108
	v_mul_f32_e32 v58, 0xbfb8aa3b, v4
	v_exp_f32_e32 v106, v59
	v_mul_f32_e32 v59, 0xbfb8aa3b, v0
	v_exp_f32_e32 v58, v58
	v_exp_f32_e32 v59, v59
	s_nop 0
	v_pk_add_f32 v[58:59], v[58:59], 1.0 op_sel_hi:[1,0]
	s_nop 0
	s_nop 0
	v_rcp_f32_e32 v107, v59
	s_nop 0
	v_mul_f32_e32 v59, v0, v107
	s_nop 0
	v_rcp_f32_e32 v0, v58
	s_nop 0
	v_mul_f32_e32 v58, v4, v0
	v_mul_f32_e32 v0, 0xbfb8aa3b, v92
	v_exp_f32_e32 v107, v0
	s_nop 0
	v_pk_add_f32 v[106:107], v[106:107], 1.0 op_sel_hi:[1,0]
	s_nop 0
	s_nop 0
	v_rcp_f32_e32 v0, v107
	s_nop 0
	v_mul_f32_e32 v107, v92, v0
	s_mov_b32 s0, 0x3727c5ac
	v_rcp_f32_e32 v0, v106
	s_nop 0
	v_mul_f32_e32 v106, v108, v0
	v_add_f32_e32 v0, v94, v96
	v_add_f32_e32 v0, v95, v0
	v_add_f32_e32 v0, v97, v0
	v_add_f32_e32 v0, v103, v0
	v_add_f32_e32 v0, v102, v0
	v_add_f32_e32 v0, v105, v0
	v_add_f32_e32 v0, v104, v0
	v_and_b32_e32 v94, 0xffff0000, v42
	s_nop 0
	v_add_f32_dpp v0, v0, v0 quad_perm:[1,0,3,2] row_mask:0xf bank_mask:0xf bound_ctrl:1
	s_nop 1
	v_add_f32_dpp v0, v0, v0 quad_perm:[2,3,0,1] row_mask:0xf bank_mask:0xf bound_ctrl:1
	s_nop 1
	v_add_f32_dpp v0, v0, v0 row_half_mirror row_mask:0xf bank_mask:0xf bound_ctrl:1
	s_nop 1
	v_add_f32_dpp v0, v0, v0 row_ror:8 row_mask:0xf bank_mask:0xf bound_ctrl:1
	ds_swizzle_b32 v4, v0 offset:swizzle(SWAP,16)
	s_waitcnt lgkmcnt(0)
; __device__ __forceinline__ unsigned pk2(float lo, float hi) { return f2bf(lo) | (f2bf(hi) << 16); }
; __device__ __forceinline__ void p3b_finalize(Frame& F, bool dummy, int gw, int NGW, int MEND) {
;     ...
;         for (int h = 0; h < 4; ++h) {
;             const float x[8] = {bflo(raw[h].x), bfhi(raw[h].x), bflo(raw[h].y), bfhi(raw[h].y), bflo(raw[h].z), bfhi(raw[h].z), bflo(raw[h].w), bfhi(raw[h].w)};
;             const float gg[8] = {bflo(gr[h].x), bfhi(gr[h].x), bflo(gr[h].y), bfhi(gr[h].y), bflo(gr[h].z), bfhi(gr[h].z), bflo(gr[h].w), bfhi(gr[h].w)};
;             float ss = 0.f;
; #pragma unroll
;             for (int e = 0; e < 8; ++e) ss += x[e] * x[e];
;             ss = wave_sum(ss); const float rs = rsqrtf(ss * (1.f / 512.f) + LN_EPS);
;             float y[8];
; #pragma unroll
;             for (int e = 0; e < 8; ++e) { const float gn = e < 4 ? g0[e & 3] : g1[e & 3]; const float sl = gg[e] / (1.f + __expf(-gg[e])); y[e] = x[e] * rs * gn * sl; }
;             bf16* p = (dummy ? (bf16*)(F.ws + WS_C) : MIXIN) + (size_t)m * 4096 + 2048 + h * 512 + 8 * lane;
;             *(v4u*)p = (v4u){pk2(y[0], y[1]), pk2(y[2], y[3]), pk2(y[4], y[5]), pk2(y[6], y[7])};
;         }
	v_add_f32_e32 v4, v0, v4
	v_mov_b32_e32 v92, v4
	s_nop 1
	v_permlane32_swap_b32_e32 v4, v92
	v_pk_add_f32 v[92:93], v[4:5], v[92:93]
	v_mov_b64_e32 v[4:5], s[0:1]
	v_pk_fma_f32 v[92:93], v[92:93], s[20:21], v[4:5] op_sel_hi:[1,0,0]
	s_nop 0
	v_mul_f32_e32 v0, 0x4b800000, v93
	v_cmp_gt_f32_e64 s[0:1], s92, v93
	v_cmp_gt_f32_e32 vcc, s92, v92
	s_nop 0
	v_cndmask_b32_e64 v0, v93, v0, s[0:1]
	v_rsq_f32_e32 v0, v0
	s_nop 0
	v_mul_f32_e32 v93, 0x45800000, v0
	v_cndmask_b32_e64 v0, v0, v93, s[0:1]
	v_pk_mul_f32 v[82:83], v[0:1], v[82:83] op_sel_hi:[0,1]
	v_pk_mul_f32 v[82:83], v[6:7], v[82:83]
	v_pk_mul_f32 v[68:69], v[0:1], v[68:69] op_sel_hi:[0,1]
	v_pk_mul_f32 v[64:65], v[64:65], v[82:83]
	v_pk_mul_f32 v[68:69], v[78:79], v[68:69]
	v_pk_mul_f32 v[82:83], v[0:1], v[86:87] op_sel_hi:[0,1]
	v_pk_mul_f32 v[68:69], v[84:85], v[68:69]
	v_pk_mul_f32 v[82:83], v[2:3], v[82:83]
	v_pk_mul_f32 v[70:71], v[0:1], v[70:71] op_sel_hi:[0,1]
	v_pk_mul_f32 v[66:67], v[66:67], v[82:83]
	v_pk_mul_f32 v[70:71], v[80:81], v[70:71]
	v_bfe_u32 v84, v68, 16, 1
	v_pk_mul_f32 v[70:71], v[88:89], v[70:71]
	v_add3_u32 v68, v68, v84, s42
	v_bfe_u32 v84, v67, 16, 1
	v_bfe_u32 v0, v71, 16, 1
	v_add3_u32 v67, v67, v84, s42
	v_add3_u32 v0, v71, v0, s42
	v_lshrrev_b32_e32 v67, 16, v67
	v_and_or_b32 v67, v0, s43, v67
	v_mul_f32_e32 v0, 0x4b800000, v92
	v_bfe_u32 v82, v70, 16, 1
	v_bfe_u32 v83, v69, 16, 1
	v_cndmask_b32_e32 v0, v92, v0, vcc
	v_add3_u32 v69, v69, v83, s42
	v_add3_u32 v70, v70, v82, s42
	v_bfe_u32 v71, v64, 16, 1
	v_bfe_u32 v82, v65, 16, 1
	v_bfe_u32 v83, v66, 16, 1
	v_rsq_f32_e32 v0, v0
	v_add3_u32 v66, v66, v83, s42
	v_add3_u32 v65, v65, v82, s42
	v_add3_u32 v64, v64, v71, s42
	v_lshrrev_b32_e32 v64, 16, v64
	v_lshrrev_b32_e32 v65, 16, v65
	v_lshrrev_b32_e32 v66, 16, v66
	v_and_or_b32 v66, v70, s43, v66
	v_and_or_b32 v65, v69, s43, v65
	v_and_or_b32 v64, v68, s43, v64
	global_store_dwordx4 v[76:77], v[64:67], off
	v_and_b32_e32 v82, 0xffff0000, v51
	v_and_b32_e32 v83, 0xffff0000, v50
	v_mul_f32_e32 v64, 0x45800000, v0
	v_cndmask_b32_e32 v0, v0, v64, vcc
	v_pk_mul_f32 v[64:65], v[0:1], v[90:91] op_sel_hi:[0,1]
	v_pk_mul_f32 v[64:65], v[6:7], v[64:65]
	v_pk_mul_f32 v[60:61], v[0:1], v[60:61] op_sel_hi:[0,1]
	v_pk_mul_f32 v[62:63], v[0:1], v[62:63] op_sel_hi:[0,1]
	v_pk_mul_f32 v[56:57], v[56:57], v[64:65]
	v_pk_mul_f32 v[60:61], v[78:79], v[60:61]
	v_pk_mul_f32 v[64:65], v[0:1], v[100:101] op_sel_hi:[0,1]
	v_pk_mul_f32 v[62:63], v[80:81], v[62:63]
	v_pk_mul_f32 v[60:61], v[98:99], v[60:61]
	v_pk_mul_f32 v[64:65], v[2:3], v[64:65]
	v_pk_mul_f32 v[62:63], v[106:107], v[62:63]
	v_pk_mul_f32 v[58:59], v[58:59], v[64:65]
	v_bfe_u32 v0, v63, 16, 1
	v_bfe_u32 v64, v62, 16, 1
	v_bfe_u32 v65, v61, 16, 1
	v_bfe_u32 v66, v60, 16, 1
	v_add3_u32 v60, v60, v66, s42
	v_add3_u32 v61, v61, v65, s42
	v_add3_u32 v62, v62, v64, s42
	v_add3_u32 v0, v63, v0, s42
	v_bfe_u32 v63, v56, 16, 1
	v_bfe_u32 v64, v57, 16, 1
	v_bfe_u32 v65, v58, 16, 1
	v_bfe_u32 v66, v59, 16, 1
	v_add3_u32 v59, v59, v66, s42
	v_add3_u32 v58, v58, v65, s42
	v_add3_u32 v57, v57, v64, s42
	v_add3_u32 v56, v56, v63, s42
	v_lshrrev_b32_e32 v56, 16, v56
	v_lshrrev_b32_e32 v57, 16, v57
	v_lshrrev_b32_e32 v58, 16, v58
	v_lshrrev_b32_e32 v59, 16, v59
	v_and_or_b32 v59, v0, s43, v59
	v_and_or_b32 v58, v62, s43, v58
	v_and_or_b32 v57, v61, s43, v57
	v_and_or_b32 v56, v60, s43, v56
	v_and_b32_e32 v61, 0xffff0000, v48
	global_store_dwordx4 v[76:77], v[56:59], off offset:1024
	v_lshlrev_b32_e32 v0, 16, v49
	v_and_b32_e32 v60, 0xffff0000, v49
	v_lshlrev_b32_e32 v59, 16, v48
	v_mul_f32_e32 v49, 0xbfb8aa3b, v61
	v_mul_f32_e32 v48, 0xbfb8aa3b, v59
	v_exp_f32_e32 v58, v49
	v_mul_f32_e32 v49, 0xbfb8aa3b, v0
	v_exp_f32_e32 v48, v48
	v_exp_f32_e32 v49, v49
	v_lshlrev_b32_e32 v57, 16, v53
	v_lshlrev_b32_e32 v56, 16, v52
	v_and_b32_e32 v53, 0xffff0000, v53
	v_pk_add_f32 v[48:49], v[48:49], 1.0 op_sel_hi:[1,0]
	v_and_b32_e32 v52, 0xffff0000, v52
	v_pk_mul_f32 v[64:65], v[56:57], v[56:57]
	v_pk_mul_f32 v[66:67], v[52:53], v[52:53]
	v_rcp_f32_e32 v62, v49
	s_nop 0
	v_mul_f32_e32 v49, v0, v62
	s_nop 0
	v_rcp_f32_e32 v0, v48
	s_nop 0
	v_mul_f32_e32 v48, v59, v0
	v_mul_f32_e32 v0, 0xbfb8aa3b, v60
	v_exp_f32_e32 v59, v0
	s_nop 0
	v_pk_add_f32 v[58:59], v[58:59], 1.0 op_sel_hi:[1,0]
	s_nop 0
	s_nop 0
	v_rcp_f32_e32 v0, v59
	s_nop 0
	v_mul_f32_e32 v59, v60, v0
	s_nop 0
	v_lshlrev_b32_e32 v60, 16, v54
	v_and_b32_e32 v54, 0xffff0000, v54
	v_rcp_f32_e32 v0, v58
	s_nop 0
	v_mul_f32_e32 v58, v61, v0
	v_lshlrev_b32_e32 v61, 16, v55
	v_and_b32_e32 v55, 0xffff0000, v55
	v_lshlrev_b32_e32 v0, 16, v51
	v_lshlrev_b32_e32 v63, 16, v50
	v_mov_b32_e32 v50, v54
	v_mov_b32_e32 v51, v60
	v_pk_mul_f32 v[68:69], v[50:51], v[50:51]
	v_mov_b32_e32 v50, v55
	v_mov_b32_e32 v51, v61
	v_pk_mul_f32 v[70:71], v[50:51], v[50:51]
	v_mul_f32_e32 v51, 0xbfb8aa3b, v83
	v_mul_f32_e32 v50, 0xbfb8aa3b, v63
	v_exp_f32_e32 v62, v51
	v_mul_f32_e32 v51, 0xbfb8aa3b, v0
	v_exp_f32_e32 v50, v50
	v_exp_f32_e32 v51, v51
	s_nop 0
	v_pk_add_f32 v[50:51], v[50:51], 1.0 op_sel_hi:[1,0]
	s_nop 0
	s_nop 0
	v_rcp_f32_e32 v84, v51
	s_nop 0
	v_mul_f32_e32 v51, v0, v84
	s_nop 0
	v_rcp_f32_e32 v0, v50
	s_nop 0
	v_mul_f32_e32 v50, v63, v0
	v_mul_f32_e32 v0, 0xbfb8aa3b, v82
	v_exp_f32_e32 v63, v0
	s_nop 0
	v_pk_add_f32 v[62:63], v[62:63], 1.0 op_sel_hi:[1,0]
	s_nop 0
	s_nop 0
	v_rcp_f32_e32 v0, v63
	s_nop 0
	v_mul_f32_e32 v63, v82, v0
	s_nop 0
	v_rcp_f32_e32 v0, v62
	s_nop 0
	v_mul_f32_e32 v62, v83, v0
	v_add_f32_e32 v0, v64, v66
	v_add_f32_e32 v0, v65, v0
	v_add_f32_e32 v0, v67, v0
	v_add_f32_e32 v0, v69, v0
	v_add_f32_e32 v0, v68, v0
	v_add_f32_e32 v0, v71, v0
	v_add_f32_e32 v0, v70, v0
	v_and_b32_e32 v86, 0xffff0000, v40
	v_lshlrev_b32_e32 v66, 16, v40
	v_add_f32_dpp v0, v0, v0 quad_perm:[1,0,3,2] row_mask:0xf bank_mask:0xf bound_ctrl:1
	v_and_b32_e32 v68, 0xffff0000, v41
	v_mul_f32_e32 v40, 0xbfb8aa3b, v66
	v_add_f32_dpp v0, v0, v0 quad_perm:[2,3,0,1] row_mask:0xf bank_mask:0xf bound_ctrl:1
	v_exp_f32_e32 v40, v40
	v_lshlrev_b32_e32 v65, 16, v45
	v_add_f32_dpp v0, v0, v0 row_half_mirror row_mask:0xf bank_mask:0xf bound_ctrl:1
	v_and_b32_e32 v45, 0xffff0000, v45
	s_nop 0
	v_add_f32_dpp v0, v0, v0 row_ror:8 row_mask:0xf bank_mask:0xf bound_ctrl:1
	ds_swizzle_b32 v64, v0 offset:swizzle(SWAP,16)
	s_waitcnt lgkmcnt(0)
; __device__ __forceinline__ unsigned pk2(float lo, float hi) { return f2bf(lo) | (f2bf(hi) << 16); }
; __device__ __forceinline__ void p3b_finalize(Frame& F, bool dummy, int gw, int NGW, int MEND) {
;     ...
;     for (int m = gw; m < MEND; m += NGW) {
;         v4u raw[4], gr[4];
; #pragma unroll
;         for (int h = 0; h < 4; ++h) { raw[h] = rawn[h]; gr[h] = grn[h]; }
;         if (m + NGW < MEND) {
; #pragma unroll
;             for (int h = 0; h < 4; ++h) { rawn[h] = *(const v4u*)(MIXIN + (size_t)(m + NGW) * 4096 + 2048 + h * 512 + 8 * lane); grn[h] = *(const v4u*)(GR + (size_t)(m + NGW) * 2048 + h * 512 + 8 * lane); } }
; #pragma unroll
;         for (int h = 0; h < 4; ++h) {
;             const float x[8] = {bflo(raw[h].x), bfhi(raw[h].x), bflo(raw[h].y), bfhi(raw[h].y), bflo(raw[h].z), bfhi(raw[h].z), bflo(raw[h].w), bfhi(raw[h].w)};
;             const float gg[8] = {bflo(gr[h].x), bfhi(gr[h].x), bflo(gr[h].y), bfhi(gr[h].y), bflo(gr[h].z), bfhi(gr[h].z), bflo(gr[h].w), bfhi(gr[h].w)};
;             float ss = 0.f;
; #pragma unroll
;             for (int e = 0; e < 8; ++e) ss += x[e] * x[e];
;             ss = wave_sum(ss); const float rs = rsqrtf(ss * (1.f / 512.f) + LN_EPS);
;             float y[8];
; #pragma unroll
;             for (int e = 0; e < 8; ++e) { const float gn = e < 4 ? g0[e & 3] : g1[e & 3]; const float sl = gg[e] / (1.f + __expf(-gg[e])); y[e] = x[e] * rs * gn * sl; }
;             bf16* p = (dummy ? (bf16*)(F.ws + WS_C) : MIXIN) + (size_t)m * 4096 + 2048 + h * 512 + 8 * lane;
;             *(v4u*)p = (v4u){pk2(y[0], y[1]), pk2(y[2], y[3]), pk2(y[4], y[5]), pk2(y[6], y[7])};
;         }
	v_add_f32_e32 v67, v0, v64
	v_lshlrev_b32_e32 v0, 16, v41
	v_mul_f32_e32 v41, 0xbfb8aa3b, v86
	v_exp_f32_e32 v84, v41
	v_mul_f32_e32 v41, 0xbfb8aa3b, v0
	v_exp_f32_e32 v41, v41
	v_lshlrev_b32_e32 v64, 16, v44
	v_and_b32_e32 v44, 0xffff0000, v44
	v_pk_mul_f32 v[70:71], v[64:65], v[64:65]
	v_pk_add_f32 v[40:41], v[40:41], 1.0 op_sel_hi:[1,0]
	v_pk_mul_f32 v[82:83], v[44:45], v[44:45]
	v_mov_b32_e32 v69, v67
	s_nop 1
	v_permlane32_swap_b32_e32 v67, v69
	v_rcp_f32_e32 v85, v41
	s_nop 0
	v_mul_f32_e32 v41, v0, v85
	s_nop 0
	v_rcp_f32_e32 v0, v40
	s_nop 0
	v_mul_f32_e32 v40, v66, v0
	v_mul_f32_e32 v0, 0xbfb8aa3b, v68
	v_exp_f32_e32 v85, v0
	s_nop 0
	v_pk_add_f32 v[84:85], v[84:85], 1.0 op_sel_hi:[1,0]
	s_nop 0
	s_nop 0
	v_rcp_f32_e32 v0, v85
	s_nop 0
	v_mul_f32_e32 v85, v68, v0
	s_nop 0
	v_rcp_f32_e32 v0, v84
	s_nop 0
	v_mul_f32_e32 v84, v86, v0
	v_lshlrev_b32_e32 v86, 16, v46
	v_and_b32_e32 v46, 0xffff0000, v46
	v_lshlrev_b32_e32 v87, 16, v47
	v_and_b32_e32 v47, 0xffff0000, v47
	v_lshlrev_b32_e32 v0, 16, v43
	v_lshlrev_b32_e32 v66, 16, v42
	v_and_b32_e32 v68, 0xffff0000, v43
	v_mov_b32_e32 v42, v46
	v_mov_b32_e32 v43, v86
	v_pk_mul_f32 v[88:89], v[42:43], v[42:43]
	v_mov_b32_e32 v42, v47
	v_mov_b32_e32 v43, v87
	v_pk_mul_f32 v[90:91], v[42:43], v[42:43]
	v_mul_f32_e32 v43, 0xbfb8aa3b, v94
	v_mul_f32_e32 v42, 0xbfb8aa3b, v66
	v_exp_f32_e32 v92, v43
	v_mul_f32_e32 v43, 0xbfb8aa3b, v0
	v_exp_f32_e32 v42, v42
	v_exp_f32_e32 v43, v43
	s_nop 0
	v_pk_add_f32 v[42:43], v[42:43], 1.0 op_sel_hi:[1,0]
	s_nop 0
	s_nop 0
	v_rcp_f32_e32 v93, v43
	s_nop 0
	v_mul_f32_e32 v43, v0, v93
	s_nop 0
	v_rcp_f32_e32 v0, v42
	s_nop 0
	v_mul_f32_e32 v42, v66, v0
	v_mul_f32_e32 v0, 0xbfb8aa3b, v68
	v_exp_f32_e32 v93, v0
	s_nop 0
	v_pk_add_f32 v[92:93], v[92:93], 1.0 op_sel_hi:[1,0]
	s_nop 0
	s_nop 0
	v_rcp_f32_e32 v0, v93
	s_nop 0
	v_mul_f32_e32 v93, v68, v0
	s_nop 0
	v_rcp_f32_e32 v0, v92
	s_nop 0
	v_mul_f32_e32 v92, v94, v0
	v_add_f32_e32 v0, v70, v82
	v_add_f32_e32 v0, v71, v0
	v_add_f32_e32 v0, v83, v0
	v_add_f32_e32 v0, v89, v0
	v_add_f32_e32 v0, v88, v0
	v_add_f32_e32 v0, v91, v0
	v_add_f32_e32 v0, v90, v0
	s_nop 1
	v_add_f32_dpp v0, v0, v0 quad_perm:[1,0,3,2] row_mask:0xf bank_mask:0xf bound_ctrl:1
	s_nop 1
	v_add_f32_dpp v0, v0, v0 quad_perm:[2,3,0,1] row_mask:0xf bank_mask:0xf bound_ctrl:1
	s_nop 1
	v_add_f32_dpp v0, v0, v0 row_half_mirror row_mask:0xf bank_mask:0xf bound_ctrl:1
	s_nop 1
	v_add_f32_dpp v0, v0, v0 row_ror:8 row_mask:0xf bank_mask:0xf bound_ctrl:1
	ds_swizzle_b32 v66, v0 offset:swizzle(SWAP,16)
	s_waitcnt lgkmcnt(0)
	v_add_f32_e32 v66, v0, v66
	v_mov_b32_e32 v68, v66
	s_nop 1
	v_permlane32_swap_b32_e32 v66, v68
	v_pk_add_f32 v[66:67], v[66:67], v[68:69]
	s_waitcnt vmcnt(3)
	v_mov_b64_e32 v[70:71], v[34:35]
	v_pk_fma_f32 v[4:5], v[66:67], s[20:21], v[4:5] op_sel_hi:[1,0,0]
	v_mov_b64_e32 v[68:69], v[32:33]
	v_mul_f32_e32 v0, 0x4b800000, v5
	v_cmp_gt_f32_e64 s[0:1], s92, v5
	v_cmp_gt_f32_e32 vcc, s92, v4
	s_nop 0
	v_cndmask_b32_e64 v0, v5, v0, s[0:1]
	v_rsq_f32_e32 v0, v0
	s_nop 0
	v_mul_f32_e32 v5, 0x45800000, v0
	v_cndmask_b32_e64 v0, v0, v5, s[0:1]
	v_pk_mul_f32 v[56:57], v[0:1], v[56:57] op_sel_hi:[0,1]
	v_pk_mul_f32 v[56:57], v[6:7], v[56:57]
	v_pk_mul_f32 v[52:53], v[0:1], v[52:53] op_sel_hi:[0,1]
	v_pk_mul_f32 v[48:49], v[48:49], v[56:57]
	v_pk_mul_f32 v[52:53], v[78:79], v[52:53]
	v_pk_mul_f32 v[56:57], v[0:1], v[60:61] op_sel_hi:[0,1]
	v_pk_mul_f32 v[52:53], v[58:59], v[52:53]
	v_pk_mul_f32 v[56:57], v[2:3], v[56:57]
	v_pk_mul_f32 v[54:55], v[0:1], v[54:55] op_sel_hi:[0,1]
	v_pk_mul_f32 v[50:51], v[50:51], v[56:57]
	v_pk_mul_f32 v[54:55], v[80:81], v[54:55]
	v_bfe_u32 v57, v52, 16, 1
	v_pk_mul_f32 v[54:55], v[62:63], v[54:55]
	v_add3_u32 v52, v52, v57, s42
	v_bfe_u32 v57, v51, 16, 1
	v_bfe_u32 v0, v55, 16, 1
	v_add3_u32 v51, v51, v57, s42
	v_add3_u32 v0, v55, v0, s42
	v_lshrrev_b32_e32 v51, 16, v51
	v_and_or_b32 v51, v0, s43, v51
	v_mul_f32_e32 v0, 0x4b800000, v4
	v_cndmask_b32_e32 v0, v4, v0, vcc
	v_rsq_f32_e32 v0, v0
	v_bfe_u32 v56, v53, 16, 1
	v_add3_u32 v53, v53, v56, s42
	v_bfe_u32 v56, v50, 16, 1
	v_bfe_u32 v5, v54, 16, 1
	v_add3_u32 v50, v50, v56, s42
	v_mul_f32_e32 v4, 0x45800000, v0
	v_add3_u32 v5, v54, v5, s42
	v_lshrrev_b32_e32 v50, 16, v50
	v_cndmask_b32_e32 v0, v0, v4, vcc
	v_and_or_b32 v50, v5, s43, v50
	v_pk_mul_f32 v[4:5], v[0:1], v[64:65] op_sel_hi:[0,1]
	v_pk_mul_f32 v[4:5], v[6:7], v[4:5]
	v_bfe_u32 v54, v48, 16, 1
	v_pk_mul_f32 v[4:5], v[40:41], v[4:5]
	v_pk_mul_f32 v[40:41], v[0:1], v[44:45] op_sel_hi:[0,1]
	v_pk_mul_f32 v[44:45], v[0:1], v[86:87] op_sel_hi:[0,1]
	v_bfe_u32 v55, v49, 16, 1
	v_pk_mul_f32 v[44:45], v[2:3], v[44:45]
	v_add3_u32 v49, v49, v55, s42
	v_add3_u32 v48, v48, v54, s42
	v_pk_mul_f32 v[42:43], v[42:43], v[44:45]
	v_pk_mul_f32 v[44:45], v[0:1], v[46:47] op_sel_hi:[0,1]
	v_lshrrev_b32_e32 v48, 16, v48
	v_lshrrev_b32_e32 v49, 16, v49
	v_pk_mul_f32 v[40:41], v[78:79], v[40:41]
	v_pk_mul_f32 v[44:45], v[80:81], v[44:45]
	v_and_or_b32 v49, v53, s43, v49
	v_and_or_b32 v48, v52, s43, v48
	v_pk_mul_f32 v[40:41], v[84:85], v[40:41]
	v_pk_mul_f32 v[44:45], v[92:93], v[44:45]
	global_store_dwordx4 v[76:77], v[48:51], off offset:2048
	v_bfe_u32 v0, v45, 16, 1
	v_bfe_u32 v46, v44, 16, 1
	v_bfe_u32 v47, v41, 16, 1
	v_bfe_u32 v48, v40, 16, 1
	v_add3_u32 v40, v40, v48, s42
	v_add3_u32 v41, v41, v47, s42
	v_add3_u32 v44, v44, v46, s42
	v_add3_u32 v0, v45, v0, s42
	v_bfe_u32 v45, v4, 16, 1
	v_bfe_u32 v46, v5, 16, 1
	v_bfe_u32 v47, v42, 16, 1
	v_bfe_u32 v48, v43, 16, 1
	v_add3_u32 v43, v43, v48, s42
	v_add3_u32 v42, v42, v47, s42
	v_add3_u32 v5, v5, v46, s42
	v_add3_u32 v4, v4, v45, s42
	v_lshrrev_b32_e32 v4, 16, v4
	v_lshrrev_b32_e32 v5, 16, v5
	v_lshrrev_b32_e32 v42, 16, v42
	v_lshrrev_b32_e32 v43, 16, v43
	v_and_or_b32 v43, v0, s43, v43
	v_and_or_b32 v42, v44, s43, v42
	v_and_or_b32 v41, v41, s43, v5
	v_and_or_b32 v40, v40, s43, v4
	global_store_dwordx4 v[76:77], v[40:43], off offset:3072
	s_mov_b64 s[0:1], 0x10000
	v_mov_b64_e32 v[66:67], v[14:15]
	v_mov_b64_e32 v[58:59], v[10:11]
	v_mov_b64_e32 v[50:51], v[22:23]
	s_waitcnt vmcnt(4)
	v_mov_b64_e32 v[42:43], v[30:31]
	v_mov_b64_e32 v[62:63], v[18:19]
	v_mov_b64_e32 v[54:55], v[26:27]
	v_mov_b64_e32 v[46:47], v[38:39]
	v_lshl_add_u64 v[76:77], v[76:77], 0, s[0:1]
	s_andn2_b64 vcc, exec, s[4:5]
	v_mov_b64_e32 v[64:65], v[12:13]
	v_mov_b64_e32 v[56:57], v[8:9]
	v_mov_b64_e32 v[48:49], v[20:21]
	v_mov_b64_e32 v[40:41], v[28:29]
	v_mov_b64_e32 v[60:61], v[16:17]
	v_mov_b64_e32 v[52:53], v[24:25]
	v_mov_b64_e32 v[44:45], v[36:37]
	s_cbranch_vccz .LBB0_1114
